# R2/R3 fast bodies: the 8 waves of a workgroup (8 consecutive rows, same batch) fetch the iteration's gate/shift/scale chunks once into LDS by LDS-DMA (3 chunks per wave, double-buffered, one s_barrier
# baseline (speedup 1.0000x reference)
; __device__ __forceinline__ float bflo(unsigned w) { return __uint_as_float(w << 16); }
; __device__ __forceinline__ void row_pass(const RowPass& R, int gw, int ngw, int lane) {
;     constexpr int NR = 2;
;     for (int row0 = gw; row0 < M; row0 += NR * ngw) {
;         f32x4 v[NR][4]; u32x2 yw[NR][4]; bool act[NR]; float* xrow[NR]; int bbs[NR];
; #pragma unroll
;         for (int k = 0; k < NR; ++k) {
;             const int row = row0 + k * ngw;
;             const int rowc = row < M ? row : row0;
;             const int b = rowc / RPB, i = rowc - b * RPB; const bool isctx = i < CTXL;
;             act[k] = (row < M) && !(isctx && R.skip_ctx);
;             bbs[k] = isctx ? 8 : b;
;             xrow[k] = isctx ? R.xc + ((size_t)b * CTXL + i) * DM : R.out + ((size_t)b * SEQ + (i - CTXL)) * DM;
;             const float* src = R.init ? (isctx ? R.ctx_in + ((size_t)b * CTXL + i) * DM : R.x_in + ((size_t)b * SEQ + (i - CTXL)) * DM) : xrow[k];
;             if (act[k]) {
; #pragma unroll
;                 for (int j = 0; j < 4; ++j) v[k][j] = __builtin_nontemporal_load((const f32x4*)(src + lane * 4 + 256 * j));
;                 if (R.update) { const bf16* yr = R.Y + (size_t)rowc * DM;
; #pragma unroll
;                     for (int j = 0; j < 4; ++j) yw[k][j] = __builtin_nontemporal_load((const u32x2*)(yr + lane * 4 + 256 * j)); }
;             }
;         }
; #pragma unroll
;         for (int k = 0; k < NR; ++k) {
;             if (!act[k]) continue;
;             const int row = row0 + k * ngw, bb = bbs[k];
;             if (R.update) {
;                 f32x4 y[4]; float ss = 0.f;
; #pragma unroll
;                 for (int j = 0; j < 4; ++j) { const u32x2 w = yw[k][j]; y[j] = (f32x4){bflo(w.x), bfhi(w.x), bflo(w.y), bfhi(w.y)};
;                     ss += (y[j][0] * y[j][0] + y[j][1] * y[j][1]) + (y[j][2] * y[j][2] + y[j][3] * y[j][3]); }
;                 const float rstd = __builtin_amdgcn_rsqf(wave_sum(ss) * (1.0f / DM) + EPS);
;                 const float* gate = R.mod + ((size_t)(R.lg * 9 + bb) * NMOD + R.gi) * DM;
; #pragma unroll
;                 for (int j = 0; j < 4; ++j) { const f32x4 g = *(const f32x4*)(gate + lane * 4 + 256 * j), gp = *(const f32x4*)(R.gpost + lane * 4 + 256 * j);
;                     v[k][j] = v[k][j] + g * (y[j] * rstd * gp); }
.LBB0_128:
	s_cmp_gt_i32 s84, 2
	s_mov_b64 s[4:5], -1
	s_cbranch_scc0 .LBB0_141
	s_cmp_gt_i32 s36, 0x87ff
	s_cbranch_scc1 .LBB0_140
	s_sub_i32 s3, s57, 30
	s_load_dwordx2 s[4:5], s[0:1], 0xa0
	s_load_dwordx4 s[8:11], s[0:1], 0x38
	s_cmp_lt_u32 s3, -7
	s_cselect_b64 s[62:63], -1, 0
	s_lshl_b32 s6, s12, 10
	s_ashr_i32 s7, s6, 31
	s_lshl_b64 s[6:7], s[6:7], 2
	s_waitcnt lgkmcnt(0)
	s_add_u32 s10, s10, s6
	s_addc_u32 s11, s11, s7
	s_add_u32 s6, s8, s6
	s_addc_u32 s7, s9, s7
	s_waitcnt vmcnt(0)
	v_lshlrev_b32_e32 v0, 4, v216
	v_mov_b32_e32 v1, v161
	s_ashr_i32 s37, s36, 31
	v_lshl_add_u64 v[42:43], s[6:7], 0, v[0:1]
	s_lshl_b64 s[6:7], s[36:37], 11
	s_add_u32 s6, s28, s6
	v_lshlrev_b32_e32 v160, 3, v216
	s_addc_u32 s7, s29, s7
	v_lshl_add_u64 v[44:45], s[10:11], 0, v[0:1]
	v_lshl_add_u64 v[0:1], s[6:7], 0, v[160:161]
	s_mov_b64 s[6:7], 0xa7fa600
	v_lshlrev_b32_e32 v36, 2, v216
	v_lshl_add_u64 v[38:39], s[20:21], 0, v[160:161]
	v_lshl_add_u64 v[40:41], s[60:61], 0, v[160:161]
	s_mul_i32 s3, s12, 9
	v_lshl_add_u64 v[46:47], v[0:1], 0, s[6:7]
	s_mov_b32 s93, 0
	global_load_dwordx4 v[218:221], v[42:43], off
	global_load_dwordx4 v[222:225], v[42:43], off offset:1024
	global_load_dwordx4 v[226:229], v[42:43], off offset:2048
	global_load_dwordx4 v[230:233], v[42:43], off offset:3072
	global_load_dwordx4 v[234:237], v[44:45], off
	global_load_dwordx4 v[238:241], v[44:45], off offset:1024
	global_load_dwordx4 v[242:245], v[44:45], off offset:2048
	global_load_dwordx4 v[246:249], v[44:45], off offset:3072
	s_mov_b32 s13, s36
	s_branch .LBB0_132

; __device__ __forceinline__ float bflo(unsigned w) { return __uint_as_float(w << 16); }
; __device__ __forceinline__ float bfhi(unsigned w) { return __uint_as_float(w & 0xffff0000u); }
; __device__ __forceinline__ void row_pass(const RowPass& R, int gw, int ngw, int lane) {
;     ...
;     for (int row0 = gw; row0 < M; row0 += NR * ngw) {
;         f32x4 v[NR][4]; u32x2 yw[NR][4]; bool act[NR]; float* xrow[NR]; int bbs[NR];
; #pragma unroll
;         for (int k = 0; k < NR; ++k) {
;             const int row = row0 + k * ngw;
;             const int rowc = row < M ? row : row0;
;             const int b = rowc / RPB, i = rowc - b * RPB; const bool isctx = i < CTXL;
;             act[k] = (row < M) && !(isctx && R.skip_ctx);
;             bbs[k] = isctx ? 8 : b;
;             xrow[k] = isctx ? R.xc + ((size_t)b * CTXL + i) * DM : R.out + ((size_t)b * SEQ + (i - CTXL)) * DM;
;             const float* src = R.init ? (isctx ? R.ctx_in + ((size_t)b * CTXL + i) * DM : R.x_in + ((size_t)b * SEQ + (i - CTXL)) * DM) : xrow[k];
;             if (act[k]) {
; #pragma unroll
;                 for (int j = 0; j < 4; ++j) v[k][j] = __builtin_nontemporal_load((const f32x4*)(src + lane * 4 + 256 * j));
;                 if (R.update) { const bf16* yr = R.Y + (size_t)rowc * DM;
; #pragma unroll
;                     for (int j = 0; j < 4; ++j) yw[k][j] = __builtin_nontemporal_load((const u32x2*)(yr + lane * 4 + 256 * j)); }
;             }
;         }
; #pragma unroll
;         for (int k = 0; k < NR; ++k) {
;             if (!act[k]) continue;
;             const int row = row0 + k * ngw, bb = bbs[k];
;             if (R.update) {
;                 f32x4 y[4]; float ss = 0.f;
; #pragma unroll
;                 for (int j = 0; j < 4; ++j) { const u32x2 w = yw[k][j]; y[j] = (f32x4){bflo(w.x), bfhi(w.x), bflo(w.y), bfhi(w.y)};
;                     ss += (y[j][0] * y[j][0] + y[j][1] * y[j][1]) + (y[j][2] * y[j][2] + y[j][3] * y[j][3]); }
;                 const float rstd = __builtin_amdgcn_rsqf(wave_sum(ss) * (1.0f / DM) + EPS);
;                 const float* gate = R.mod + ((size_t)(R.lg * 9 + bb) * NMOD + R.gi) * DM;
; #pragma unroll
;                 for (int j = 0; j < 4; ++j) { const f32x4 g = *(const f32x4*)(gate + lane * 4 + 256 * j), gp = *(const f32x4*)(R.gpost + lane * 4 + 256 * j);
;                     v[k][j] = v[k][j] + g * (y[j] * rstd * gp); }
.LBB0_132:
	s_mul_hi_i32 s6, s13, 0x78787879
	s_lshr_b32 s7, s6, 31
	s_ashr_i32 s6, s6, 11
	s_add_i32 s6, s6, s7
	s_mul_i32 s7, s6, 0xffffef00
	s_add_i32 s7, s13, s7
	s_cmpk_gt_i32 s7, 0xff
	s_cselect_b64 s[50:51], -1, 0
	s_add_i32 s8, s44, s13
	s_cmp_lt_i32 s8, 0x8800
	s_cbranch_scc0 .Lr2_slow
	s_mul_hi_i32 s9, s8, 0x78787879
	s_lshr_b32 s25, s9, 31
	s_ashr_i32 s9, s9, 11
	s_add_i32 s9, s9, s25
	s_mul_i32 s25, s9, 0xffffef00
	s_add_i32 s25, s8, s25
	s_cmpk_gt_i32 s25, 0xff
	s_cselect_b64 s[52:53], -1, 0
	s_and_b64 s[46:47], s[50:51], s[52:53]
	s_or_b64 s[46:47], s[46:47], s[62:63]
	s_cmp_lg_u64 s[46:47], 0
	s_cbranch_scc0 .Lr2_slow
	v_lshlrev_b32_e32 v160, 2, v36
	s_add_i32 s72, s7, 0xffffff00
	s_cmp_lg_u64 s[50:51], 0
	s_cselect_b32 s27, s4, s49
	s_cselect_b32 s32, s5, s55
	s_cselect_b32 s37, 24, 20
	s_cselect_b32 s72, s72, s7
	s_cselect_b32 s85, s6, 8
	s_mov_b32 s40, s6
	s_mov_b32 s41, 0
	s_lshl_b64 s[40:41], s[40:41], s37
	s_add_u32 s40, s27, s40
	s_addc_u32 s41, s32, s41
	s_lshl_b32 s72, s72, 12
	s_add_u32 s40, s40, s72
	s_addc_u32 s41, s41, 0
	s_add_i32 s27, s85, s3
	s_mul_hi_i32 s32, s27, 0x6000
	s_mulk_i32 s27, 0x6000
	s_add_u32 s66, s34, s27
	s_addc_u32 s67, s35, s32
	s_add_u32 s66, s66, 0x2000
	s_addc_u32 s67, s67, 0
	s_add_i32 s27, s85, s3
	s_mul_hi_i32 s32, s27, 0x6000
	s_mulk_i32 s27, 0x6000
	s_add_u32 s38, s34, s27
	s_addc_u32 s39, s35, s32
	s_add_u32 s38, s38, 0x3000
	s_addc_u32 s39, s39, 0
	s_add_u32 s46, s38, 0x1000
	s_addc_u32 s47, s39, 0
	global_load_dwordx4 v[12:15], v160, s[40:41] nt
	global_load_dwordx4 v[8:11], v160, s[40:41] offset:1024 nt
	global_load_dwordx4 v[4:7], v160, s[40:41] offset:2048 nt
	global_load_dwordx4 v[0:3], v160, s[40:41] offset:3072 nt
	global_load_dwordx2 v[54:55], v[46:47], off offset:-1536 nt
	global_load_dwordx2 v[52:53], v[46:47], off offset:-1024 nt
	global_load_dwordx2 v[50:51], v[46:47], off offset:-512 nt
	global_load_dwordx2 v[48:49], v[46:47], off nt
	s_mov_b32 s6, s8
	s_ashr_i32 s7, s8, 31
	s_lshl_b64 s[6:7], s[6:7], 11
	v_lshl_add_u64 v[250:251], v[38:39], 0, s[6:7]
	v_lshl_add_u64 v[252:253], v[40:41], 0, s[6:7]
	s_mov_b64 s[6:7], s[52:53]
	s_add_i32 s72, s25, 0xffffff00
	s_cmp_lg_u64 s[6:7], 0
	s_cselect_b32 s27, s4, s49
	s_cselect_b32 s32, s5, s55
	s_cselect_b32 s37, 24, 20
	s_cselect_b32 s72, s72, s25
	s_cselect_b32 s85, s9, 8
	s_mov_b32 s64, s9
	s_mov_b32 s65, 0
	s_lshl_b64 s[64:65], s[64:65], s37
	s_add_u32 s64, s27, s64
	s_addc_u32 s65, s32, s65
	s_lshl_b32 s72, s72, 12
	s_add_u32 s64, s64, s72
	s_addc_u32 s65, s65, 0
	s_add_i32 s27, s85, s3
	s_mul_hi_i32 s32, s27, 0x6000
	s_mulk_i32 s27, 0x6000
	s_add_u32 s10, s34, s27
	s_addc_u32 s11, s35, s32
	s_add_u32 s10, s10, 0x2000
	s_addc_u32 s11, s11, 0
	s_add_i32 s27, s85, s3
	s_mul_hi_i32 s32, s27, 0x6000
	s_mulk_i32 s27, 0x6000
	s_add_u32 s50, s34, s27
	s_addc_u32 s51, s35, s32
	s_add_u32 s50, s50, 0x3000
	s_addc_u32 s51, s51, 0
	s_add_u32 s52, s50, 0x1000
	s_addc_u32 s53, s51, 0
	s_and_b32 s72, s13, 7
	s_and_b32 s85, s72, 3
	s_lshl_b32 s85, s85, 10
	s_lshl_b32 s37, s72, 10
	s_add_i32 s37, s37, s93
	s_cmp_lt_u32 s72, 4
	s_cselect_b32 s6, s66, s38
	s_cselect_b32 s7, s67, s39
	s_cselect_b32 s8, s46, s10
	s_cselect_b32 s9, s47, s11
	s_cselect_b32 s26, s50, s52
	s_cselect_b32 s27, s51, s53
	s_add_u32 s6, s6, s85
	s_addc_u32 s7, s7, 0
	s_add_u32 s8, s8, s85
	s_addc_u32 s9, s9, 0
	s_add_u32 s26, s26, s85
	s_addc_u32 s27, s27, 0
	s_mov_b32 m0, s37
	s_nop 0
	global_load_lds_dwordx4 v160, s[6:7]
	s_add_i32 s37, s37, 0x2000
	s_mov_b32 m0, s37
	s_nop 0
	global_load_lds_dwordx4 v160, s[8:9]
	s_add_i32 s37, s37, 0x2000
	s_mov_b32 m0, s37
	s_nop 0
	global_load_lds_dwordx4 v160, s[26:27]
	global_load_dwordx4 v[16:19], v160, s[64:65] nt
	global_load_dwordx4 v[20:23], v160, s[64:65] offset:1024 nt
	global_load_dwordx4 v[24:27], v160, s[64:65] offset:2048 nt
	global_load_dwordx4 v[28:31], v160, s[64:65] offset:3072 nt
	global_load_dwordx2 v[62:63], v[250:251], off nt
	global_load_dwordx2 v[60:61], v[250:251], off offset:512 nt
	global_load_dwordx2 v[58:59], v[250:251], off offset:1024 nt
	global_load_dwordx2 v[56:57], v[250:251], off offset:1536 nt
	s_waitcnt vmcnt(8)
	s_barrier
	v_add_u32_e32 v37, s93, v160
	ds_read_b128 v[64:67], v37
	ds_read_b128 v[68:71], v37 offset:1024
	ds_read_b128 v[72:75], v37 offset:2048
	ds_read_b128 v[76:79], v37 offset:3072
	ds_read_b128 v[80:83], v37 offset:4096
	ds_read_b128 v[84:87], v37 offset:5120
	ds_read_b128 v[88:91], v37 offset:6144
	ds_read_b128 v[92:95], v37 offset:7168
	ds_read_b128 v[172:175], v37 offset:8192
	ds_read_b128 v[176:179], v37 offset:9216
	ds_read_b128 v[180:183], v37 offset:10240
	ds_read_b128 v[184:187], v37 offset:11264
	s_waitcnt vmcnt(11)
; __device__ __forceinline__ unsigned pk2(float lo, float hi) { return pg8::cvt_pk_bf16(lo, hi); }
; __device__ __forceinline__ float bflo(unsigned w) { return __uint_as_float(w << 16); }
; __device__ __forceinline__ float bfhi(unsigned w) { return __uint_as_float(w & 0xffff0000u); }
; __device__ __forceinline__ void row_pass(const RowPass& R, int gw, int ngw, int lane) {
;     ...
;             if (R.update) {
;                 f32x4 y[4]; float ss = 0.f;
; #pragma unroll
;                 for (int j = 0; j < 4; ++j) { const u32x2 w = yw[k][j]; y[j] = (f32x4){bflo(w.x), bfhi(w.x), bflo(w.y), bfhi(w.y)};
;                     ss += (y[j][0] * y[j][0] + y[j][1] * y[j][1]) + (y[j][2] * y[j][2] + y[j][3] * y[j][3]); }
;                 const float rstd = __builtin_amdgcn_rsqf(wave_sum(ss) * (1.0f / DM) + EPS);
;                 const float* gate = R.mod + ((size_t)(R.lg * 9 + bb) * NMOD + R.gi) * DM;
; #pragma unroll
;                 for (int j = 0; j < 4; ++j) { const f32x4 g = *(const f32x4*)(gate + lane * 4 + 256 * j), gp = *(const f32x4*)(R.gpost + lane * 4 + 256 * j);
;                     v[k][j] = v[k][j] + g * (y[j] * rstd * gp); }
;             }
;             if (R.init || R.update) {
; #pragma unroll
;                 for (int j = 0; j < 4; ++j) __builtin_nontemporal_store(v[k][j], (f32x4*)(xrow[k] + lane * 4 + 256 * j));
;             }
;             if (R.norm_out) {
;                 float ss = 0.f;
; #pragma unroll
;                 for (int j = 0; j < 4; ++j) ss += (v[k][j][0] * v[k][j][0] + v[k][j][1] * v[k][j][1]) + (v[k][j][2] * v[k][j][2] + v[k][j][3] * v[k][j][3]);
;                 const float rstd = __builtin_amdgcn_rsqf(wave_sum(ss) * (1.0f / DM) + EPS);
;                 const float* shift = R.mod + ((size_t)(R.ln * 9 + bb) * NMOD + R.si) * DM; const float* scale = shift + DM;
;                 bf16* hr = R.H + (size_t)row * DM;
; #pragma unroll
;                 for (int j = 0; j < 4; ++j) { const f32x4 gp = *(const f32x4*)(R.gpre + lane * 4 + 256 * j), sh = *(const f32x4*)(shift + lane * 4 + 256 * j), sc = *(const f32x4*)(scale + lane * 4 + 256 * j);
;                     const f32x4 hv = (v[k][j] * rstd * gp) * (sc + 1.0f) + sh;
;                     u32x2 w; w.x = pk2(hv[0], hv[1]); w.y = pk2(hv[2], hv[3]); *(u32x2*)(hr + lane * 4 + 256 * j) = w; }
	v_lshlrev_b32_e32 v32, 16, v54
	v_and_b32_e32 v33, 0xffff0000, v54
	v_lshlrev_b32_e32 v34, 16, v55
	v_and_b32_e32 v35, 0xffff0000, v55
	v_pk_mul_f32 v[166:167], v[32:33], v[32:33]
	v_pk_mul_f32 v[168:169], v[34:35], v[34:35]
	v_lshlrev_b32_e32 v32, 16, v52
	v_and_b32_e32 v33, 0xffff0000, v52
	v_lshlrev_b32_e32 v34, 16, v53
	v_and_b32_e32 v35, 0xffff0000, v53
	v_pk_fma_f32 v[166:167], v[32:33], v[32:33], v[166:167]
	v_pk_fma_f32 v[168:169], v[34:35], v[34:35], v[168:169]
	v_lshlrev_b32_e32 v32, 16, v50
	v_and_b32_e32 v33, 0xffff0000, v50
	v_lshlrev_b32_e32 v34, 16, v51
	v_and_b32_e32 v35, 0xffff0000, v51
	v_pk_fma_f32 v[166:167], v[32:33], v[32:33], v[166:167]
	v_pk_fma_f32 v[168:169], v[34:35], v[34:35], v[168:169]
	v_lshlrev_b32_e32 v32, 16, v48
	v_and_b32_e32 v33, 0xffff0000, v48
	v_lshlrev_b32_e32 v34, 16, v49
	v_and_b32_e32 v35, 0xffff0000, v49
	v_pk_fma_f32 v[166:167], v[32:33], v[32:33], v[166:167]
	v_pk_fma_f32 v[168:169], v[34:35], v[34:35], v[168:169]
	v_pk_add_f32 v[166:167], v[166:167], v[168:169]
	s_nop 0
	v_add_f32_e32 v164, v166, v167
	v_mov_b32_e32 v165, v164
	s_nop 1
	v_permlane32_swap_b32_e32 v165, v164
	v_add_f32_e32 v164, v164, v165
	v_mov_b32_e32 v165, v164
	s_nop 1
	v_permlane16_swap_b32_e32 v165, v164
	v_add_f32_e32 v164, v164, v165
	s_nop 1
	v_add_f32_dpp v164, v164, v164 row_ror:8 row_mask:0xf bank_mask:0xf
	s_nop 1
	v_add_f32_dpp v164, v164, v164 row_ror:4 row_mask:0xf bank_mask:0xf
	s_nop 1
	v_add_f32_dpp v164, v164, v164 row_ror:2 row_mask:0xf bank_mask:0xf
	s_nop 1
	v_add_f32_dpp v164, v164, v164 row_ror:1 row_mask:0xf bank_mask:0xf
	s_nop 0
	v_fmamk_f32 v164, v164, 0x3a800000, v200
	v_rsq_f32_e32 v164, v164
	v_lshlrev_b32_e32 v32, 16, v54
	v_and_b32_e32 v33, 0xffff0000, v54
	v_lshlrev_b32_e32 v34, 16, v55
	v_and_b32_e32 v35, 0xffff0000, v55
	v_pk_mul_f32 v[32:33], v[32:33], v[164:165] op_sel_hi:[1,0]
	v_pk_mul_f32 v[34:35], v[34:35], v[164:165] op_sel_hi:[1,0]
	v_pk_mul_f32 v[32:33], v[218:219], v[32:33]
	v_pk_mul_f32 v[34:35], v[220:221], v[34:35]
	s_waitcnt lgkmcnt(11)
	v_pk_fma_f32 v[12:13], v[64:65], v[32:33], v[12:13]
	v_pk_fma_f32 v[14:15], v[66:67], v[34:35], v[14:15]
	global_store_dwordx4 v160, v[12:15], s[40:41] nt
	v_lshlrev_b32_e32 v32, 16, v52
	v_and_b32_e32 v33, 0xffff0000, v52
	v_lshlrev_b32_e32 v34, 16, v53
	v_and_b32_e32 v35, 0xffff0000, v53
	v_pk_mul_f32 v[32:33], v[32:33], v[164:165] op_sel_hi:[1,0]
	v_pk_mul_f32 v[34:35], v[34:35], v[164:165] op_sel_hi:[1,0]
	v_pk_mul_f32 v[32:33], v[222:223], v[32:33]
	v_pk_mul_f32 v[34:35], v[224:225], v[34:35]
	s_waitcnt lgkmcnt(10)
	v_pk_fma_f32 v[8:9], v[68:69], v[32:33], v[8:9]
	v_pk_fma_f32 v[10:11], v[70:71], v[34:35], v[10:11]
	global_store_dwordx4 v160, v[8:11], s[40:41] offset:1024 nt
	v_lshlrev_b32_e32 v32, 16, v50
	v_and_b32_e32 v33, 0xffff0000, v50
	v_lshlrev_b32_e32 v34, 16, v51
	v_and_b32_e32 v35, 0xffff0000, v51
	v_pk_mul_f32 v[32:33], v[32:33], v[164:165] op_sel_hi:[1,0]
	v_pk_mul_f32 v[34:35], v[34:35], v[164:165] op_sel_hi:[1,0]
	v_pk_mul_f32 v[32:33], v[226:227], v[32:33]
	v_pk_mul_f32 v[34:35], v[228:229], v[34:35]
	s_waitcnt lgkmcnt(9)
	v_pk_fma_f32 v[4:5], v[72:73], v[32:33], v[4:5]
	v_pk_fma_f32 v[6:7], v[74:75], v[34:35], v[6:7]
	global_store_dwordx4 v160, v[4:7], s[40:41] offset:2048 nt
	v_lshlrev_b32_e32 v32, 16, v48
	v_and_b32_e32 v33, 0xffff0000, v48
	v_lshlrev_b32_e32 v34, 16, v49
	v_and_b32_e32 v35, 0xffff0000, v49
	v_pk_mul_f32 v[32:33], v[32:33], v[164:165] op_sel_hi:[1,0]
	v_pk_mul_f32 v[34:35], v[34:35], v[164:165] op_sel_hi:[1,0]
	v_pk_mul_f32 v[32:33], v[230:231], v[32:33]
	v_pk_mul_f32 v[34:35], v[232:233], v[34:35]
	s_waitcnt lgkmcnt(8)
	v_pk_fma_f32 v[0:1], v[76:77], v[32:33], v[0:1]
	v_pk_fma_f32 v[2:3], v[78:79], v[34:35], v[2:3]
	global_store_dwordx4 v160, v[0:3], s[40:41] offset:3072 nt
	s_waitcnt lgkmcnt(0)
	ds_read_b128 v[188:191], v37 offset:12288
	ds_read_b128 v[192:195], v37 offset:13312
	ds_read_b128 v[196:199], v37 offset:14336
	ds_read_b128 v[96:99], v37 offset:15360
	ds_read_b128 v[64:67], v37 offset:16384
	ds_read_b128 v[68:71], v37 offset:17408
	ds_read_b128 v[72:75], v37 offset:18432
	ds_read_b128 v[76:79], v37 offset:19456
	v_add_co_u32_e32 v250, vcc, 0xfbc00000, v46
	v_addc_co_u32_e32 v251, vcc, -1, v47, vcc
	v_pk_mul_f32 v[166:167], v[12:13], v[12:13]
	v_pk_mul_f32 v[168:169], v[14:15], v[14:15]
	v_pk_fma_f32 v[166:167], v[8:9], v[8:9], v[166:167]
	v_pk_fma_f32 v[168:169], v[10:11], v[10:11], v[168:169]
	v_pk_fma_f32 v[166:167], v[4:5], v[4:5], v[166:167]
	v_pk_fma_f32 v[168:169], v[6:7], v[6:7], v[168:169]
	v_pk_fma_f32 v[166:167], v[0:1], v[0:1], v[166:167]
	v_pk_fma_f32 v[168:169], v[2:3], v[2:3], v[168:169]
	v_pk_add_f32 v[166:167], v[166:167], v[168:169]
	s_nop 0
	v_add_f32_e32 v164, v166, v167
	v_mov_b32_e32 v165, v164
	s_nop 1
	v_permlane32_swap_b32_e32 v165, v164
	v_add_f32_e32 v164, v164, v165
	v_mov_b32_e32 v165, v164
	s_nop 1
	v_permlane16_swap_b32_e32 v165, v164
	v_add_f32_e32 v164, v164, v165
	s_nop 1
	v_add_f32_dpp v164, v164, v164 row_ror:8 row_mask:0xf bank_mask:0xf
	s_nop 1
	v_add_f32_dpp v164, v164, v164 row_ror:4 row_mask:0xf bank_mask:0xf
	s_nop 1
	v_add_f32_dpp v164, v164, v164 row_ror:2 row_mask:0xf bank_mask:0xf
	s_nop 1
	v_add_f32_dpp v164, v164, v164 row_ror:1 row_mask:0xf bank_mask:0xf
	s_nop 0
	v_fmamk_f32 v164, v164, 0x3a800000, v200
	v_rsq_f32_e32 v164, v164
	s_nop 0
	v_pk_mul_f32 v[12:13], v[12:13], v[164:165] op_sel_hi:[1,0]
	v_pk_mul_f32 v[14:15], v[14:15], v[164:165] op_sel_hi:[1,0]
	v_pk_mul_f32 v[12:13], v[234:235], v[12:13]
	v_pk_mul_f32 v[14:15], v[236:237], v[14:15]
	v_pk_add_f32 v[172:173], v[172:173], 1.0 op_sel_hi:[1,0]
	v_pk_add_f32 v[174:175], v[174:175], 1.0 op_sel_hi:[1,0]
; __device__ __forceinline__ unsigned pk2(float lo, float hi) { return pg8::cvt_pk_bf16(lo, hi); }
; __device__ __forceinline__ float bflo(unsigned w) { return __uint_as_float(w << 16); }
; __device__ __forceinline__ float bfhi(unsigned w) { return __uint_as_float(w & 0xffff0000u); }
; __device__ __forceinline__ void row_pass(const RowPass& R, int gw, int ngw, int lane) {
;     ...
;             if (R.update) {
;                 f32x4 y[4]; float ss = 0.f;
; #pragma unroll
;                 for (int j = 0; j < 4; ++j) { const u32x2 w = yw[k][j]; y[j] = (f32x4){bflo(w.x), bfhi(w.x), bflo(w.y), bfhi(w.y)};
;                     ss += (y[j][0] * y[j][0] + y[j][1] * y[j][1]) + (y[j][2] * y[j][2] + y[j][3] * y[j][3]); }
;                 const float rstd = __builtin_amdgcn_rsqf(wave_sum(ss) * (1.0f / DM) + EPS);
;                 const float* gate = R.mod + ((size_t)(R.lg * 9 + bb) * NMOD + R.gi) * DM;
; #pragma unroll
;                 for (int j = 0; j < 4; ++j) { const f32x4 g = *(const f32x4*)(gate + lane * 4 + 256 * j), gp = *(const f32x4*)(R.gpost + lane * 4 + 256 * j);
;                     v[k][j] = v[k][j] + g * (y[j] * rstd * gp); }
;             }
;     ...
;             if (R.norm_out) {
;                 float ss = 0.f;
; #pragma unroll
;                 for (int j = 0; j < 4; ++j) ss += (v[k][j][0] * v[k][j][0] + v[k][j][1] * v[k][j][1]) + (v[k][j][2] * v[k][j][2] + v[k][j][3] * v[k][j][3]);
;                 const float rstd = __builtin_amdgcn_rsqf(wave_sum(ss) * (1.0f / DM) + EPS);
;                 const float* shift = R.mod + ((size_t)(R.ln * 9 + bb) * NMOD + R.si) * DM; const float* scale = shift + DM;
;                 bf16* hr = R.H + (size_t)row * DM;
; #pragma unroll
;                 for (int j = 0; j < 4; ++j) { const f32x4 gp = *(const f32x4*)(R.gpre + lane * 4 + 256 * j), sh = *(const f32x4*)(shift + lane * 4 + 256 * j), sc = *(const f32x4*)(scale + lane * 4 + 256 * j);
;                     const f32x4 hv = (v[k][j] * rstd * gp) * (sc + 1.0f) + sh;
;                     u32x2 w; w.x = pk2(hv[0], hv[1]); w.y = pk2(hv[2], hv[3]); *(u32x2*)(hr + lane * 4 + 256 * j) = w; }
	v_pk_fma_f32 v[12:13], v[172:173], v[12:13], v[80:81]
	v_pk_fma_f32 v[14:15], v[174:175], v[14:15], v[82:83]
	v_cvt_pk_bf16_f32 v12, v12, v13
	v_cvt_pk_bf16_f32 v13, v14, v15
	global_store_dwordx2 v[250:251], v[12:13], off offset:-1536
	ds_read_b128 v[80:83], v37 offset:20480
	v_pk_mul_f32 v[8:9], v[8:9], v[164:165] op_sel_hi:[1,0]
	v_pk_mul_f32 v[10:11], v[10:11], v[164:165] op_sel_hi:[1,0]
	v_pk_mul_f32 v[8:9], v[238:239], v[8:9]
	v_pk_mul_f32 v[10:11], v[240:241], v[10:11]
	v_pk_add_f32 v[176:177], v[176:177], 1.0 op_sel_hi:[1,0]
	v_pk_add_f32 v[178:179], v[178:179], 1.0 op_sel_hi:[1,0]
	v_pk_fma_f32 v[8:9], v[176:177], v[8:9], v[84:85]
	v_pk_fma_f32 v[10:11], v[178:179], v[10:11], v[86:87]
	v_cvt_pk_bf16_f32 v8, v8, v9
	v_cvt_pk_bf16_f32 v9, v10, v11
	global_store_dwordx2 v[250:251], v[8:9], off offset:-1024
	ds_read_b128 v[84:87], v37 offset:21504
	v_pk_mul_f32 v[4:5], v[4:5], v[164:165] op_sel_hi:[1,0]
	v_pk_mul_f32 v[6:7], v[6:7], v[164:165] op_sel_hi:[1,0]
	v_pk_mul_f32 v[4:5], v[242:243], v[4:5]
	v_pk_mul_f32 v[6:7], v[244:245], v[6:7]
	v_pk_add_f32 v[180:181], v[180:181], 1.0 op_sel_hi:[1,0]
	v_pk_add_f32 v[182:183], v[182:183], 1.0 op_sel_hi:[1,0]
	v_pk_fma_f32 v[4:5], v[180:181], v[4:5], v[88:89]
	v_pk_fma_f32 v[6:7], v[182:183], v[6:7], v[90:91]
	v_cvt_pk_bf16_f32 v4, v4, v5
	v_cvt_pk_bf16_f32 v5, v6, v7
	global_store_dwordx2 v[250:251], v[4:5], off offset:-512
	ds_read_b128 v[88:91], v37 offset:22528
	v_pk_mul_f32 v[0:1], v[0:1], v[164:165] op_sel_hi:[1,0]
	v_pk_mul_f32 v[2:3], v[2:3], v[164:165] op_sel_hi:[1,0]
	v_pk_mul_f32 v[0:1], v[246:247], v[0:1]
	v_pk_mul_f32 v[2:3], v[248:249], v[2:3]
	v_pk_add_f32 v[184:185], v[184:185], 1.0 op_sel_hi:[1,0]
	v_pk_add_f32 v[186:187], v[186:187], 1.0 op_sel_hi:[1,0]
	v_pk_fma_f32 v[0:1], v[184:185], v[0:1], v[92:93]
	v_pk_fma_f32 v[2:3], v[186:187], v[2:3], v[94:95]
	v_cvt_pk_bf16_f32 v0, v0, v1
	v_cvt_pk_bf16_f32 v1, v2, v3
	global_store_dwordx2 v[250:251], v[0:1], off
	ds_read_b128 v[92:95], v37 offset:23552
	s_waitcnt vmcnt(8)
	v_lshlrev_b32_e32 v32, 16, v62
	v_and_b32_e32 v33, 0xffff0000, v62
	v_lshlrev_b32_e32 v34, 16, v63
	v_and_b32_e32 v35, 0xffff0000, v63
	v_pk_mul_f32 v[166:167], v[32:33], v[32:33]
	v_pk_mul_f32 v[168:169], v[34:35], v[34:35]
	v_lshlrev_b32_e32 v32, 16, v60
	v_and_b32_e32 v33, 0xffff0000, v60
	v_lshlrev_b32_e32 v34, 16, v61
	v_and_b32_e32 v35, 0xffff0000, v61
	v_pk_fma_f32 v[166:167], v[32:33], v[32:33], v[166:167]
	v_pk_fma_f32 v[168:169], v[34:35], v[34:35], v[168:169]
	v_lshlrev_b32_e32 v32, 16, v58
	v_and_b32_e32 v33, 0xffff0000, v58
	v_lshlrev_b32_e32 v34, 16, v59
	v_and_b32_e32 v35, 0xffff0000, v59
	v_pk_fma_f32 v[166:167], v[32:33], v[32:33], v[166:167]
	v_pk_fma_f32 v[168:169], v[34:35], v[34:35], v[168:169]
	v_lshlrev_b32_e32 v32, 16, v56
	v_and_b32_e32 v33, 0xffff0000, v56
	v_lshlrev_b32_e32 v34, 16, v57
	v_and_b32_e32 v35, 0xffff0000, v57
	v_pk_fma_f32 v[166:167], v[32:33], v[32:33], v[166:167]
	v_pk_fma_f32 v[168:169], v[34:35], v[34:35], v[168:169]
	v_pk_add_f32 v[166:167], v[166:167], v[168:169]
	s_nop 0
	v_add_f32_e32 v164, v166, v167
	v_mov_b32_e32 v165, v164
	s_nop 1
	v_permlane32_swap_b32_e32 v165, v164
	v_add_f32_e32 v164, v164, v165
	v_mov_b32_e32 v165, v164
	s_nop 1
	v_permlane16_swap_b32_e32 v165, v164
	v_add_f32_e32 v164, v164, v165
	s_nop 1
	v_add_f32_dpp v164, v164, v164 row_ror:8 row_mask:0xf bank_mask:0xf
	s_nop 1
	v_add_f32_dpp v164, v164, v164 row_ror:4 row_mask:0xf bank_mask:0xf
	s_nop 1
	v_add_f32_dpp v164, v164, v164 row_ror:2 row_mask:0xf bank_mask:0xf
	s_nop 1
	v_add_f32_dpp v164, v164, v164 row_ror:1 row_mask:0xf bank_mask:0xf
	s_nop 0
	v_fmamk_f32 v164, v164, 0x3a800000, v200
	v_rsq_f32_e32 v164, v164
	v_lshlrev_b32_e32 v32, 16, v62
	v_and_b32_e32 v33, 0xffff0000, v62
	v_lshlrev_b32_e32 v34, 16, v63
	v_and_b32_e32 v35, 0xffff0000, v63
	v_pk_mul_f32 v[32:33], v[32:33], v[164:165] op_sel_hi:[1,0]
	v_pk_mul_f32 v[34:35], v[34:35], v[164:165] op_sel_hi:[1,0]
	v_pk_mul_f32 v[32:33], v[218:219], v[32:33]
	v_pk_mul_f32 v[34:35], v[220:221], v[34:35]
	s_waitcnt lgkmcnt(11)
	v_pk_fma_f32 v[16:17], v[188:189], v[32:33], v[16:17]
	v_pk_fma_f32 v[18:19], v[190:191], v[34:35], v[18:19]
	global_store_dwordx4 v160, v[16:19], s[64:65] nt
	v_lshlrev_b32_e32 v32, 16, v60
	v_and_b32_e32 v33, 0xffff0000, v60
	v_lshlrev_b32_e32 v34, 16, v61
	v_and_b32_e32 v35, 0xffff0000, v61
	v_pk_mul_f32 v[32:33], v[32:33], v[164:165] op_sel_hi:[1,0]
	v_pk_mul_f32 v[34:35], v[34:35], v[164:165] op_sel_hi:[1,0]
	v_pk_mul_f32 v[32:33], v[222:223], v[32:33]
	v_pk_mul_f32 v[34:35], v[224:225], v[34:35]
	s_waitcnt lgkmcnt(10)
; __device__ __forceinline__ unsigned pk2(float lo, float hi) { return pg8::cvt_pk_bf16(lo, hi); }
;     __device__ __forceinline__ void init(int N, int G, int c, int latent_only) { lat = latent_only; b.init(latent_only ? NB * SEQ : M, N, G, c); }
;     __device__ __forceinline__ void init(int c_, unsigned* cnt_) { lat.init(NB * SEQ, FF2, 1, 0); c = c_; cnt = cnt_; }
; __device__ __forceinline__ void row_pass(const RowPass& R, int gw, int ngw, int lane) {
;     ...
;                 for (int j = 0; j < 4; ++j) { const f32x4 g = *(const f32x4*)(gate + lane * 4 + 256 * j), gp = *(const f32x4*)(R.gpost + lane * 4 + 256 * j);
;                     v[k][j] = v[k][j] + g * (y[j] * rstd * gp); }
;             }
;             if (R.init || R.update) {
; #pragma unroll
;                 for (int j = 0; j < 4; ++j) __builtin_nontemporal_store(v[k][j], (f32x4*)(xrow[k] + lane * 4 + 256 * j));
;             }
;             if (R.norm_out) {
;                 float ss = 0.f;
; #pragma unroll
;                 for (int j = 0; j < 4; ++j) ss += (v[k][j][0] * v[k][j][0] + v[k][j][1] * v[k][j][1]) + (v[k][j][2] * v[k][j][2] + v[k][j][3] * v[k][j][3]);
;                 const float rstd = __builtin_amdgcn_rsqf(wave_sum(ss) * (1.0f / DM) + EPS);
;                 const float* shift = R.mod + ((size_t)(R.ln * 9 + bb) * NMOD + R.si) * DM; const float* scale = shift + DM;
;                 bf16* hr = R.H + (size_t)row * DM;
; #pragma unroll
;                 for (int j = 0; j < 4; ++j) { const f32x4 gp = *(const f32x4*)(R.gpre + lane * 4 + 256 * j), sh = *(const f32x4*)(shift + lane * 4 + 256 * j), sc = *(const f32x4*)(scale + lane * 4 + 256 * j);
;                     const f32x4 hv = (v[k][j] * rstd * gp) * (sc + 1.0f) + sh;
;                     u32x2 w; w.x = pk2(hv[0], hv[1]); w.y = pk2(hv[2], hv[3]); *(u32x2*)(hr + lane * 4 + 256 * j) = w; }
;             }
;         }
	v_pk_fma_f32 v[20:21], v[192:193], v[32:33], v[20:21]
	v_pk_fma_f32 v[22:23], v[194:195], v[34:35], v[22:23]
	global_store_dwordx4 v160, v[20:23], s[64:65] offset:1024 nt
	v_lshlrev_b32_e32 v32, 16, v58
	v_and_b32_e32 v33, 0xffff0000, v58
	v_lshlrev_b32_e32 v34, 16, v59
	v_and_b32_e32 v35, 0xffff0000, v59
	v_pk_mul_f32 v[32:33], v[32:33], v[164:165] op_sel_hi:[1,0]
	v_pk_mul_f32 v[34:35], v[34:35], v[164:165] op_sel_hi:[1,0]
	v_pk_mul_f32 v[32:33], v[226:227], v[32:33]
	v_pk_mul_f32 v[34:35], v[228:229], v[34:35]
	s_waitcnt lgkmcnt(9)
	v_pk_fma_f32 v[24:25], v[196:197], v[32:33], v[24:25]
	v_pk_fma_f32 v[26:27], v[198:199], v[34:35], v[26:27]
	global_store_dwordx4 v160, v[24:27], s[64:65] offset:2048 nt
	v_lshlrev_b32_e32 v32, 16, v56
	v_and_b32_e32 v33, 0xffff0000, v56
	v_lshlrev_b32_e32 v34, 16, v57
	v_and_b32_e32 v35, 0xffff0000, v57
	v_pk_mul_f32 v[32:33], v[32:33], v[164:165] op_sel_hi:[1,0]
	v_pk_mul_f32 v[34:35], v[34:35], v[164:165] op_sel_hi:[1,0]
	v_pk_mul_f32 v[32:33], v[230:231], v[32:33]
	v_pk_mul_f32 v[34:35], v[232:233], v[34:35]
	s_waitcnt lgkmcnt(8)
	v_pk_fma_f32 v[28:29], v[96:97], v[32:33], v[28:29]
	v_pk_fma_f32 v[30:31], v[98:99], v[34:35], v[30:31]
	global_store_dwordx4 v160, v[28:31], s[64:65] offset:3072 nt
	v_pk_mul_f32 v[166:167], v[16:17], v[16:17]
	v_pk_mul_f32 v[168:169], v[18:19], v[18:19]
	v_pk_fma_f32 v[166:167], v[20:21], v[20:21], v[166:167]
	v_pk_fma_f32 v[168:169], v[22:23], v[22:23], v[168:169]
	v_pk_fma_f32 v[166:167], v[24:25], v[24:25], v[166:167]
	v_pk_fma_f32 v[168:169], v[26:27], v[26:27], v[168:169]
	v_pk_fma_f32 v[166:167], v[28:29], v[28:29], v[166:167]
	v_pk_fma_f32 v[168:169], v[30:31], v[30:31], v[168:169]
	v_pk_add_f32 v[166:167], v[166:167], v[168:169]
	s_nop 0
	v_add_f32_e32 v164, v166, v167
	v_mov_b32_e32 v165, v164
	s_nop 1
	v_permlane32_swap_b32_e32 v165, v164
	v_add_f32_e32 v164, v164, v165
	v_mov_b32_e32 v165, v164
	s_nop 1
	v_permlane16_swap_b32_e32 v165, v164
	v_add_f32_e32 v164, v164, v165
	s_nop 1
	v_add_f32_dpp v164, v164, v164 row_ror:8 row_mask:0xf bank_mask:0xf
	s_nop 1
	v_add_f32_dpp v164, v164, v164 row_ror:4 row_mask:0xf bank_mask:0xf
	s_nop 1
	v_add_f32_dpp v164, v164, v164 row_ror:2 row_mask:0xf bank_mask:0xf
	s_nop 1
	v_add_f32_dpp v164, v164, v164 row_ror:1 row_mask:0xf bank_mask:0xf
	s_nop 0
	v_fmamk_f32 v164, v164, 0x3a800000, v200
	v_rsq_f32_e32 v164, v164
	s_nop 0
	v_pk_mul_f32 v[16:17], v[16:17], v[164:165] op_sel_hi:[1,0]
	v_pk_mul_f32 v[18:19], v[18:19], v[164:165] op_sel_hi:[1,0]
	v_pk_mul_f32 v[16:17], v[234:235], v[16:17]
	v_pk_mul_f32 v[18:19], v[236:237], v[18:19]
	s_waitcnt lgkmcnt(3)
	v_pk_add_f32 v[80:81], v[80:81], 1.0 op_sel_hi:[1,0]
	v_pk_add_f32 v[82:83], v[82:83], 1.0 op_sel_hi:[1,0]
	v_pk_fma_f32 v[16:17], v[80:81], v[16:17], v[64:65]
	v_pk_fma_f32 v[18:19], v[82:83], v[18:19], v[66:67]
	v_cvt_pk_bf16_f32 v16, v16, v17
	v_cvt_pk_bf16_f32 v17, v18, v19
	global_store_dwordx2 v[252:253], v[16:17], off
	v_pk_mul_f32 v[20:21], v[20:21], v[164:165] op_sel_hi:[1,0]
	v_pk_mul_f32 v[22:23], v[22:23], v[164:165] op_sel_hi:[1,0]
	v_pk_mul_f32 v[20:21], v[238:239], v[20:21]
	v_pk_mul_f32 v[22:23], v[240:241], v[22:23]
	s_waitcnt lgkmcnt(2)
	v_pk_add_f32 v[84:85], v[84:85], 1.0 op_sel_hi:[1,0]
	v_pk_add_f32 v[86:87], v[86:87], 1.0 op_sel_hi:[1,0]
	v_pk_fma_f32 v[20:21], v[84:85], v[20:21], v[68:69]
	v_pk_fma_f32 v[22:23], v[86:87], v[22:23], v[70:71]
	v_cvt_pk_bf16_f32 v20, v20, v21
	v_cvt_pk_bf16_f32 v21, v22, v23
	global_store_dwordx2 v[252:253], v[20:21], off offset:512
	v_pk_mul_f32 v[24:25], v[24:25], v[164:165] op_sel_hi:[1,0]
	v_pk_mul_f32 v[26:27], v[26:27], v[164:165] op_sel_hi:[1,0]
	v_pk_mul_f32 v[24:25], v[242:243], v[24:25]
	v_pk_mul_f32 v[26:27], v[244:245], v[26:27]
	s_waitcnt lgkmcnt(1)
	v_pk_add_f32 v[88:89], v[88:89], 1.0 op_sel_hi:[1,0]
	v_pk_add_f32 v[90:91], v[90:91], 1.0 op_sel_hi:[1,0]
	v_pk_fma_f32 v[24:25], v[88:89], v[24:25], v[72:73]
	v_pk_fma_f32 v[26:27], v[90:91], v[26:27], v[74:75]
	v_cvt_pk_bf16_f32 v24, v24, v25
	v_cvt_pk_bf16_f32 v25, v26, v27
	global_store_dwordx2 v[252:253], v[24:25], off offset:1024
	v_pk_mul_f32 v[28:29], v[28:29], v[164:165] op_sel_hi:[1,0]
	v_pk_mul_f32 v[30:31], v[30:31], v[164:165] op_sel_hi:[1,0]
	v_pk_mul_f32 v[28:29], v[246:247], v[28:29]
	v_pk_mul_f32 v[30:31], v[248:249], v[30:31]
	s_waitcnt lgkmcnt(0)
	v_pk_add_f32 v[92:93], v[92:93], 1.0 op_sel_hi:[1,0]
	v_pk_add_f32 v[94:95], v[94:95], 1.0 op_sel_hi:[1,0]
	v_pk_fma_f32 v[28:29], v[92:93], v[28:29], v[76:77]
	v_pk_fma_f32 v[30:31], v[94:95], v[30:31], v[78:79]
	v_cvt_pk_bf16_f32 v28, v28, v29
	v_cvt_pk_bf16_f32 v29, v30, v31
	global_store_dwordx2 v[252:253], v[28:29], off offset:1536
	s_xor_b32 s93, s93, 0x6000
	s_branch .LBB0_131

; __device__ __forceinline__ float bflo(unsigned w) { return __uint_as_float(w << 16); }
; __device__ __forceinline__ void row_pass(const RowPass& R, int gw, int ngw, int lane) {
;     constexpr int NR = 2;
;     for (int row0 = gw; row0 < M; row0 += NR * ngw) {
;         f32x4 v[NR][4]; u32x2 yw[NR][4]; bool act[NR]; float* xrow[NR]; int bbs[NR];
; #pragma unroll
;         for (int k = 0; k < NR; ++k) {
;             const int row = row0 + k * ngw;
;             const int rowc = row < M ? row : row0;
;             const int b = rowc / RPB, i = rowc - b * RPB; const bool isctx = i < CTXL;
;             act[k] = (row < M) && !(isctx && R.skip_ctx);
;             bbs[k] = isctx ? 8 : b;
;             xrow[k] = isctx ? R.xc + ((size_t)b * CTXL + i) * DM : R.out + ((size_t)b * SEQ + (i - CTXL)) * DM;
;             const float* src = R.init ? (isctx ? R.ctx_in + ((size_t)b * CTXL + i) * DM : R.x_in + ((size_t)b * SEQ + (i - CTXL)) * DM) : xrow[k];
;             if (act[k]) {
; #pragma unroll
;                 for (int j = 0; j < 4; ++j) v[k][j] = __builtin_nontemporal_load((const f32x4*)(src + lane * 4 + 256 * j));
;                 if (R.update) { const bf16* yr = R.Y + (size_t)rowc * DM;
; #pragma unroll
;                     for (int j = 0; j < 4; ++j) yw[k][j] = __builtin_nontemporal_load((const u32x2*)(yr + lane * 4 + 256 * j)); }
;             }
;         }
; #pragma unroll
;         for (int k = 0; k < NR; ++k) {
;             if (!act[k]) continue;
;             const int row = row0 + k * ngw, bb = bbs[k];
;             if (R.update) {
;                 f32x4 y[4]; float ss = 0.f;
; #pragma unroll
;                 for (int j = 0; j < 4; ++j) { const u32x2 w = yw[k][j]; y[j] = (f32x4){bflo(w.x), bfhi(w.x), bflo(w.y), bfhi(w.y)};
;                     ss += (y[j][0] * y[j][0] + y[j][1] * y[j][1]) + (y[j][2] * y[j][2] + y[j][3] * y[j][3]); }
;                 const float rstd = __builtin_amdgcn_rsqf(wave_sum(ss) * (1.0f / DM) + EPS);
;                 const float* gate = R.mod + ((size_t)(R.lg * 9 + bb) * NMOD + R.gi) * DM;
; #pragma unroll
;                 for (int j = 0; j < 4; ++j) { const f32x4 g = *(const f32x4*)(gate + lane * 4 + 256 * j), gp = *(const f32x4*)(R.gpost + lane * 4 + 256 * j);
;                     v[k][j] = v[k][j] + g * (y[j] * rstd * gp); }
.LBB0_145:
	v_readlane_b32 s6, v255, 17
	v_readlane_b32 s7, v255, 18
	s_and_b64 vcc, exec, s[6:7]
	s_cbranch_vccz .LBB0_160
	s_cmp_gt_i32 s36, 0x87ff
	s_cbranch_scc1 .LBB0_159
	s_sub_i32 s3, s57, 30
	s_cmp_lt_u32 s3, -7
	s_cselect_b64 s[4:5], -1, 0
	s_cmp_lg_u64 s[4:5], 0
	s_load_dwordx2 s[8:9], s[0:1], 0x30
	s_addc_u32 s13, s12, 0
	s_lshl_b32 s6, s13, 10
	s_ashr_i32 s7, s6, 31
	s_lshl_b64 s[6:7], s[6:7], 2
	s_load_dwordx2 s[22:23], s[0:1], 0xa0
	s_load_dwordx2 s[10:11], s[0:1], 0x48
	s_waitcnt lgkmcnt(0)
	s_add_u32 s6, s8, s6
	s_addc_u32 s7, s9, s7
	s_lshl_b32 s8, s12, 10
	s_ashr_i32 s9, s8, 31
	s_lshl_b64 s[8:9], s[8:9], 2
	s_add_u32 s8, s10, s8
	s_addc_u32 s9, s11, s9
	s_waitcnt vmcnt(0)
	v_lshlrev_b32_e32 v0, 4, v216
	v_mov_b32_e32 v1, v161
	s_ashr_i32 s37, s36, 31
	v_lshl_add_u64 v[44:45], s[6:7], 0, v[0:1]
	s_lshl_b64 s[6:7], s[36:37], 11
	s_add_u32 s6, s28, s6
	v_lshlrev_b32_e32 v160, 3, v216
	s_addc_u32 s7, s29, s7
	v_lshl_add_u64 v[42:43], s[8:9], 0, v[0:1]
	v_lshl_add_u64 v[0:1], s[6:7], 0, v[160:161]
	s_mov_b64 s[6:7], 0xa7fa600
	v_lshlrev_b32_e32 v36, 2, v216
	v_lshl_add_u64 v[38:39], s[20:21], 0, v[160:161]
	v_lshl_add_u64 v[40:41], s[60:61], 0, v[160:161]
	s_mul_i32 s3, s12, 9
	s_mul_i32 s13, s13, 9
	v_lshl_add_u64 v[46:47], v[0:1], 0, s[6:7]
	s_mov_b32 s93, 0
	global_load_dwordx4 v[218:221], v[42:43], off
	global_load_dwordx4 v[222:225], v[42:43], off offset:1024
	global_load_dwordx4 v[226:229], v[42:43], off offset:2048
	global_load_dwordx4 v[230:233], v[42:43], off offset:3072
	global_load_dwordx4 v[234:237], v[44:45], off
	global_load_dwordx4 v[238:241], v[44:45], off offset:1024
	global_load_dwordx4 v[242:245], v[44:45], off offset:2048
	global_load_dwordx4 v[246:249], v[44:45], off offset:3072
	s_mov_b32 s19, s36
	s_branch .LBB0_149

; __device__ __forceinline__ float bflo(unsigned w) { return __uint_as_float(w << 16); }
; __device__ __forceinline__ float bfhi(unsigned w) { return __uint_as_float(w & 0xffff0000u); }
; __device__ __forceinline__ void row_pass(const RowPass& R, int gw, int ngw, int lane) {
;     ...
;     for (int row0 = gw; row0 < M; row0 += NR * ngw) {
;         f32x4 v[NR][4]; u32x2 yw[NR][4]; bool act[NR]; float* xrow[NR]; int bbs[NR];
; #pragma unroll
;         for (int k = 0; k < NR; ++k) {
;             const int row = row0 + k * ngw;
;             const int rowc = row < M ? row : row0;
;             const int b = rowc / RPB, i = rowc - b * RPB; const bool isctx = i < CTXL;
;             act[k] = (row < M) && !(isctx && R.skip_ctx);
;             bbs[k] = isctx ? 8 : b;
;             xrow[k] = isctx ? R.xc + ((size_t)b * CTXL + i) * DM : R.out + ((size_t)b * SEQ + (i - CTXL)) * DM;
;             const float* src = R.init ? (isctx ? R.ctx_in + ((size_t)b * CTXL + i) * DM : R.x_in + ((size_t)b * SEQ + (i - CTXL)) * DM) : xrow[k];
;             if (act[k]) {
; #pragma unroll
;                 for (int j = 0; j < 4; ++j) v[k][j] = __builtin_nontemporal_load((const f32x4*)(src + lane * 4 + 256 * j));
;                 if (R.update) { const bf16* yr = R.Y + (size_t)rowc * DM;
; #pragma unroll
;                     for (int j = 0; j < 4; ++j) yw[k][j] = __builtin_nontemporal_load((const u32x2*)(yr + lane * 4 + 256 * j)); }
;             }
;         }
; #pragma unroll
;         for (int k = 0; k < NR; ++k) {
;             if (!act[k]) continue;
;             const int row = row0 + k * ngw, bb = bbs[k];
;             if (R.update) {
;                 f32x4 y[4]; float ss = 0.f;
; #pragma unroll
;                 for (int j = 0; j < 4; ++j) { const u32x2 w = yw[k][j]; y[j] = (f32x4){bflo(w.x), bfhi(w.x), bflo(w.y), bfhi(w.y)};
;                     ss += (y[j][0] * y[j][0] + y[j][1] * y[j][1]) + (y[j][2] * y[j][2] + y[j][3] * y[j][3]); }
;                 const float rstd = __builtin_amdgcn_rsqf(wave_sum(ss) * (1.0f / DM) + EPS);
;                 const float* gate = R.mod + ((size_t)(R.lg * 9 + bb) * NMOD + R.gi) * DM;
; #pragma unroll
;                 for (int j = 0; j < 4; ++j) { const f32x4 g = *(const f32x4*)(gate + lane * 4 + 256 * j), gp = *(const f32x4*)(R.gpost + lane * 4 + 256 * j);
;                     v[k][j] = v[k][j] + g * (y[j] * rstd * gp); }
.LBB0_149:
	s_mul_hi_i32 s6, s19, 0x78787879
	s_lshr_b32 s7, s6, 31
	s_ashr_i32 s6, s6, 11
	s_add_i32 s6, s6, s7
	s_mul_i32 s7, s6, 0xffffef00
	s_add_i32 s7, s19, s7
	s_cmpk_gt_i32 s7, 0xff
	s_cselect_b64 s[50:51], -1, 0
	s_add_i32 s8, s44, s19
	s_cmp_lt_i32 s8, 0x8800
	s_cbranch_scc0 .Lr3_slow
	s_mul_hi_i32 s9, s8, 0x78787879
	s_lshr_b32 s25, s9, 31
	s_ashr_i32 s9, s9, 11
	s_add_i32 s9, s9, s25
	s_mul_i32 s25, s9, 0xffffef00
	s_add_i32 s25, s8, s25
	s_cmpk_gt_i32 s25, 0xff
	s_cselect_b64 s[52:53], -1, 0
	s_cmp_lg_u64 s[4:5], 0
	s_cbranch_scc0 .Lr3_slow_u
	v_lshlrev_b32_e32 v160, 2, v36
	s_add_i32 s72, s7, 0xffffff00
	s_cmp_lg_u64 s[50:51], 0
	s_cselect_b32 s27, s22, s49
	s_cselect_b32 s32, s23, s55
	s_cselect_b32 s37, 24, 20
	s_cselect_b32 s72, s72, s7
	s_cselect_b32 s85, s6, 8
	s_mov_b32 s40, s6
	s_mov_b32 s41, 0
	s_lshl_b64 s[40:41], s[40:41], s37
	s_add_u32 s40, s27, s40
	s_addc_u32 s41, s32, s41
	s_lshl_b32 s72, s72, 12
	s_add_u32 s40, s40, s72
	s_addc_u32 s41, s41, 0
	s_add_i32 s27, s85, s3
	s_mul_hi_i32 s32, s27, 0x6000
	s_mulk_i32 s27, 0x6000
	s_add_u32 s66, s34, s27
	s_addc_u32 s67, s35, s32
	s_add_u32 s66, s66, 0x5000
	s_addc_u32 s67, s67, 0
	s_add_i32 s27, s85, s13
	s_mul_hi_i32 s32, s27, 0x6000
	s_mulk_i32 s27, 0x6000
	s_add_u32 s38, s34, s27
	s_addc_u32 s39, s35, s32
	s_add_u32 s46, s38, 0x1000
	s_addc_u32 s47, s39, 0
	global_load_dwordx4 v[12:15], v160, s[40:41] nt
	global_load_dwordx4 v[8:11], v160, s[40:41] offset:1024 nt
	global_load_dwordx4 v[4:7], v160, s[40:41] offset:2048 nt
	global_load_dwordx4 v[0:3], v160, s[40:41] offset:3072 nt
	global_load_dwordx2 v[54:55], v[46:47], off offset:-1536 nt
	global_load_dwordx2 v[52:53], v[46:47], off offset:-1024 nt
	global_load_dwordx2 v[50:51], v[46:47], off offset:-512 nt
	global_load_dwordx2 v[48:49], v[46:47], off nt
	s_mov_b32 s6, s8
	s_ashr_i32 s7, s8, 31
	s_lshl_b64 s[6:7], s[6:7], 11
	v_lshl_add_u64 v[250:251], v[38:39], 0, s[6:7]
	v_lshl_add_u64 v[252:253], v[40:41], 0, s[6:7]
	s_mov_b64 s[6:7], s[52:53]
	s_add_i32 s72, s25, 0xffffff00
	s_cmp_lg_u64 s[6:7], 0
	s_cselect_b32 s27, s22, s49
	s_cselect_b32 s32, s23, s55
	s_cselect_b32 s37, 24, 20
	s_cselect_b32 s72, s72, s25
	s_cselect_b32 s85, s9, 8
	s_mov_b32 s64, s9
	s_mov_b32 s65, 0
	s_lshl_b64 s[64:65], s[64:65], s37
	s_add_u32 s64, s27, s64
	s_addc_u32 s65, s32, s65
	s_lshl_b32 s72, s72, 12
	s_add_u32 s64, s64, s72
	s_addc_u32 s65, s65, 0
	s_add_i32 s27, s85, s3
	s_mul_hi_i32 s32, s27, 0x6000
	s_mulk_i32 s27, 0x6000
	s_add_u32 s10, s34, s27
	s_addc_u32 s11, s35, s32
	s_add_u32 s10, s10, 0x5000
	s_addc_u32 s11, s11, 0
	s_add_i32 s27, s85, s13
	s_mul_hi_i32 s32, s27, 0x6000
	s_mulk_i32 s27, 0x6000
	s_add_u32 s50, s34, s27
	s_addc_u32 s51, s35, s32
	s_add_u32 s52, s50, 0x1000
	s_addc_u32 s53, s51, 0
	s_and_b32 s72, s19, 7
	s_and_b32 s85, s72, 3
	s_lshl_b32 s85, s85, 10
	s_lshl_b32 s37, s72, 10
	s_add_i32 s37, s37, s93
	s_cmp_lt_u32 s72, 4
	s_cselect_b32 s6, s66, s38
	s_cselect_b32 s7, s67, s39
	s_cselect_b32 s8, s46, s10
	s_cselect_b32 s9, s47, s11
	s_cselect_b32 s26, s50, s52
	s_cselect_b32 s27, s51, s53
	s_add_u32 s6, s6, s85
	s_addc_u32 s7, s7, 0
	s_add_u32 s8, s8, s85
	s_addc_u32 s9, s9, 0
	s_add_u32 s26, s26, s85
	s_addc_u32 s27, s27, 0
	s_mov_b32 m0, s37
	s_nop 0
	global_load_lds_dwordx4 v160, s[6:7]
	s_add_i32 s37, s37, 0x2000
	s_mov_b32 m0, s37
	s_nop 0
	global_load_lds_dwordx4 v160, s[8:9]
	s_add_i32 s37, s37, 0x2000
	s_mov_b32 m0, s37
	s_nop 0
	global_load_lds_dwordx4 v160, s[26:27]
	global_load_dwordx4 v[16:19], v160, s[64:65] nt
	global_load_dwordx4 v[20:23], v160, s[64:65] offset:1024 nt
	global_load_dwordx4 v[24:27], v160, s[64:65] offset:2048 nt
	global_load_dwordx4 v[28:31], v160, s[64:65] offset:3072 nt
	global_load_dwordx2 v[62:63], v[250:251], off nt
	global_load_dwordx2 v[60:61], v[250:251], off offset:512 nt
	global_load_dwordx2 v[58:59], v[250:251], off offset:1024 nt
	global_load_dwordx2 v[56:57], v[250:251], off offset:1536 nt
	s_waitcnt vmcnt(8)
	s_barrier
	v_add_u32_e32 v37, s93, v160
	ds_read_b128 v[64:67], v37
	ds_read_b128 v[68:71], v37 offset:1024
	ds_read_b128 v[72:75], v37 offset:2048
	ds_read_b128 v[76:79], v37 offset:3072
	ds_read_b128 v[80:83], v37 offset:4096
	ds_read_b128 v[84:87], v37 offset:5120
	ds_read_b128 v[88:91], v37 offset:6144
	ds_read_b128 v[92:95], v37 offset:7168
	ds_read_b128 v[172:175], v37 offset:8192
	ds_read_b128 v[176:179], v37 offset:9216
	ds_read_b128 v[180:183], v37 offset:10240
	ds_read_b128 v[184:187], v37 offset:11264
	s_waitcnt vmcnt(11)
	v_lshlrev_b32_e32 v32, 16, v54
	v_and_b32_e32 v33, 0xffff0000, v54
	v_lshlrev_b32_e32 v34, 16, v55
	v_and_b32_e32 v35, 0xffff0000, v55
	v_pk_mul_f32 v[166:167], v[32:33], v[32:33]
	v_pk_mul_f32 v[168:169], v[34:35], v[34:35]
	v_lshlrev_b32_e32 v32, 16, v52
	v_and_b32_e32 v33, 0xffff0000, v52
	v_lshlrev_b32_e32 v34, 16, v53
	v_and_b32_e32 v35, 0xffff0000, v53
	v_pk_fma_f32 v[166:167], v[32:33], v[32:33], v[166:167]
	v_pk_fma_f32 v[168:169], v[34:35], v[34:35], v[168:169]
	v_lshlrev_b32_e32 v32, 16, v50
	v_and_b32_e32 v33, 0xffff0000, v50
	v_lshlrev_b32_e32 v34, 16, v51
	v_and_b32_e32 v35, 0xffff0000, v51
	v_pk_fma_f32 v[166:167], v[32:33], v[32:33], v[166:167]
	v_pk_fma_f32 v[168:169], v[34:35], v[34:35], v[168:169]
	v_lshlrev_b32_e32 v32, 16, v48
	v_and_b32_e32 v33, 0xffff0000, v48
	v_lshlrev_b32_e32 v34, 16, v49
	v_and_b32_e32 v35, 0xffff0000, v49
	v_pk_fma_f32 v[166:167], v[32:33], v[32:33], v[166:167]
	v_pk_fma_f32 v[168:169], v[34:35], v[34:35], v[168:169]
	v_pk_add_f32 v[166:167], v[166:167], v[168:169]
	s_nop 0
	v_add_f32_e32 v164, v166, v167
	v_mov_b32_e32 v165, v164
	s_nop 1
	v_permlane32_swap_b32_e32 v165, v164
	v_add_f32_e32 v164, v164, v165
	v_mov_b32_e32 v165, v164
	s_nop 1
	v_permlane16_swap_b32_e32 v165, v164
	v_add_f32_e32 v164, v164, v165
	s_nop 1
	v_add_f32_dpp v164, v164, v164 row_ror:8 row_mask:0xf bank_mask:0xf
	s_nop 1
	v_add_f32_dpp v164, v164, v164 row_ror:4 row_mask:0xf bank_mask:0xf
	s_nop 1
	v_add_f32_dpp v164, v164, v164 row_ror:2 row_mask:0xf bank_mask:0xf
	s_nop 1
	v_add_f32_dpp v164, v164, v164 row_ror:1 row_mask:0xf bank_mask:0xf
	s_nop 0
	v_fmamk_f32 v164, v164, 0x3a800000, v200
	v_rsq_f32_e32 v164, v164
	v_lshlrev_b32_e32 v32, 16, v54
	v_and_b32_e32 v33, 0xffff0000, v54
	v_lshlrev_b32_e32 v34, 16, v55
	v_and_b32_e32 v35, 0xffff0000, v55
	v_pk_mul_f32 v[32:33], v[32:33], v[164:165] op_sel_hi:[1,0]
	v_pk_mul_f32 v[34:35], v[34:35], v[164:165] op_sel_hi:[1,0]
	v_pk_mul_f32 v[32:33], v[218:219], v[32:33]
	v_pk_mul_f32 v[34:35], v[220:221], v[34:35]
	s_waitcnt lgkmcnt(11)
; __device__ __forceinline__ unsigned pk2(float lo, float hi) { return pg8::cvt_pk_bf16(lo, hi); }
;     __device__ __forceinline__ void init(int N, int G, int c, int latent_only) { lat = latent_only; b.init(latent_only ? NB * SEQ : M, N, G, c); }
;     __device__ __forceinline__ void init(int c_, unsigned* cnt_) { lat.init(NB * SEQ, FF2, 1, 0); c = c_; cnt = cnt_; }
; __device__ __forceinline__ void row_pass(const RowPass& R, int gw, int ngw, int lane) {
;     ...
;                 for (int j = 0; j < 4; ++j) { const f32x4 g = *(const f32x4*)(gate + lane * 4 + 256 * j), gp = *(const f32x4*)(R.gpost + lane * 4 + 256 * j);
;                     v[k][j] = v[k][j] + g * (y[j] * rstd * gp); }
;             }
;             if (R.init || R.update) {
; #pragma unroll
;                 for (int j = 0; j < 4; ++j) __builtin_nontemporal_store(v[k][j], (f32x4*)(xrow[k] + lane * 4 + 256 * j));
;             }
;             if (R.norm_out) {
;                 float ss = 0.f;
; #pragma unroll
;                 for (int j = 0; j < 4; ++j) ss += (v[k][j][0] * v[k][j][0] + v[k][j][1] * v[k][j][1]) + (v[k][j][2] * v[k][j][2] + v[k][j][3] * v[k][j][3]);
;                 const float rstd = __builtin_amdgcn_rsqf(wave_sum(ss) * (1.0f / DM) + EPS);
;                 const float* shift = R.mod + ((size_t)(R.ln * 9 + bb) * NMOD + R.si) * DM; const float* scale = shift + DM;
;                 bf16* hr = R.H + (size_t)row * DM;
; #pragma unroll
;                 for (int j = 0; j < 4; ++j) { const f32x4 gp = *(const f32x4*)(R.gpre + lane * 4 + 256 * j), sh = *(const f32x4*)(shift + lane * 4 + 256 * j), sc = *(const f32x4*)(scale + lane * 4 + 256 * j);
;                     const f32x4 hv = (v[k][j] * rstd * gp) * (sc + 1.0f) + sh;
;                     u32x2 w; w.x = pk2(hv[0], hv[1]); w.y = pk2(hv[2], hv[3]); *(u32x2*)(hr + lane * 4 + 256 * j) = w; }
	v_pk_fma_f32 v[12:13], v[64:65], v[32:33], v[12:13]
	v_pk_fma_f32 v[14:15], v[66:67], v[34:35], v[14:15]
	global_store_dwordx4 v160, v[12:15], s[40:41] nt
	v_lshlrev_b32_e32 v32, 16, v52
	v_and_b32_e32 v33, 0xffff0000, v52
	v_lshlrev_b32_e32 v34, 16, v53
	v_and_b32_e32 v35, 0xffff0000, v53
	v_pk_mul_f32 v[32:33], v[32:33], v[164:165] op_sel_hi:[1,0]
	v_pk_mul_f32 v[34:35], v[34:35], v[164:165] op_sel_hi:[1,0]
	v_pk_mul_f32 v[32:33], v[222:223], v[32:33]
	v_pk_mul_f32 v[34:35], v[224:225], v[34:35]
	s_waitcnt lgkmcnt(10)
	v_pk_fma_f32 v[8:9], v[68:69], v[32:33], v[8:9]
	v_pk_fma_f32 v[10:11], v[70:71], v[34:35], v[10:11]
	global_store_dwordx4 v160, v[8:11], s[40:41] offset:1024 nt
	v_lshlrev_b32_e32 v32, 16, v50
	v_and_b32_e32 v33, 0xffff0000, v50
	v_lshlrev_b32_e32 v34, 16, v51
	v_and_b32_e32 v35, 0xffff0000, v51
	v_pk_mul_f32 v[32:33], v[32:33], v[164:165] op_sel_hi:[1,0]
	v_pk_mul_f32 v[34:35], v[34:35], v[164:165] op_sel_hi:[1,0]
	v_pk_mul_f32 v[32:33], v[226:227], v[32:33]
	v_pk_mul_f32 v[34:35], v[228:229], v[34:35]
	s_waitcnt lgkmcnt(9)
	v_pk_fma_f32 v[4:5], v[72:73], v[32:33], v[4:5]
	v_pk_fma_f32 v[6:7], v[74:75], v[34:35], v[6:7]
	global_store_dwordx4 v160, v[4:7], s[40:41] offset:2048 nt
	v_lshlrev_b32_e32 v32, 16, v48
	v_and_b32_e32 v33, 0xffff0000, v48
	v_lshlrev_b32_e32 v34, 16, v49
	v_and_b32_e32 v35, 0xffff0000, v49
	v_pk_mul_f32 v[32:33], v[32:33], v[164:165] op_sel_hi:[1,0]
	v_pk_mul_f32 v[34:35], v[34:35], v[164:165] op_sel_hi:[1,0]
	v_pk_mul_f32 v[32:33], v[230:231], v[32:33]
	v_pk_mul_f32 v[34:35], v[232:233], v[34:35]
	s_waitcnt lgkmcnt(8)
	v_pk_fma_f32 v[0:1], v[76:77], v[32:33], v[0:1]
	v_pk_fma_f32 v[2:3], v[78:79], v[34:35], v[2:3]
	global_store_dwordx4 v160, v[0:3], s[40:41] offset:3072 nt
	s_waitcnt lgkmcnt(0)
	ds_read_b128 v[188:191], v37 offset:12288
	ds_read_b128 v[192:195], v37 offset:13312
	ds_read_b128 v[196:199], v37 offset:14336
	ds_read_b128 v[96:99], v37 offset:15360
	ds_read_b128 v[64:67], v37 offset:16384
	ds_read_b128 v[68:71], v37 offset:17408
	ds_read_b128 v[72:75], v37 offset:18432
	ds_read_b128 v[76:79], v37 offset:19456
	v_add_co_u32_e32 v250, vcc, 0xfbc00000, v46
	v_addc_co_u32_e32 v251, vcc, -1, v47, vcc
	v_pk_mul_f32 v[166:167], v[12:13], v[12:13]
	v_pk_mul_f32 v[168:169], v[14:15], v[14:15]
	v_pk_fma_f32 v[166:167], v[8:9], v[8:9], v[166:167]
	v_pk_fma_f32 v[168:169], v[10:11], v[10:11], v[168:169]
	v_pk_fma_f32 v[166:167], v[4:5], v[4:5], v[166:167]
	v_pk_fma_f32 v[168:169], v[6:7], v[6:7], v[168:169]
	v_pk_fma_f32 v[166:167], v[0:1], v[0:1], v[166:167]
	v_pk_fma_f32 v[168:169], v[2:3], v[2:3], v[168:169]
	v_pk_add_f32 v[166:167], v[166:167], v[168:169]
	s_nop 0
	v_add_f32_e32 v164, v166, v167
	v_mov_b32_e32 v165, v164
	s_nop 1
	v_permlane32_swap_b32_e32 v165, v164
	v_add_f32_e32 v164, v164, v165
	v_mov_b32_e32 v165, v164
	s_nop 1
	v_permlane16_swap_b32_e32 v165, v164
	v_add_f32_e32 v164, v164, v165
	s_nop 1
	v_add_f32_dpp v164, v164, v164 row_ror:8 row_mask:0xf bank_mask:0xf
	s_nop 1
	v_add_f32_dpp v164, v164, v164 row_ror:4 row_mask:0xf bank_mask:0xf
	s_nop 1
	v_add_f32_dpp v164, v164, v164 row_ror:2 row_mask:0xf bank_mask:0xf
	s_nop 1
	v_add_f32_dpp v164, v164, v164 row_ror:1 row_mask:0xf bank_mask:0xf
	s_nop 0
	v_fmamk_f32 v164, v164, 0x3a800000, v200
	v_rsq_f32_e32 v164, v164
	s_nop 0
	v_pk_mul_f32 v[12:13], v[12:13], v[164:165] op_sel_hi:[1,0]
	v_pk_mul_f32 v[14:15], v[14:15], v[164:165] op_sel_hi:[1,0]
	v_pk_mul_f32 v[12:13], v[234:235], v[12:13]
	v_pk_mul_f32 v[14:15], v[236:237], v[14:15]
	v_pk_add_f32 v[172:173], v[172:173], 1.0 op_sel_hi:[1,0]
	v_pk_add_f32 v[174:175], v[174:175], 1.0 op_sel_hi:[1,0]
	v_pk_fma_f32 v[12:13], v[172:173], v[12:13], v[80:81]
	v_pk_fma_f32 v[14:15], v[174:175], v[14:15], v[82:83]
	v_cvt_pk_bf16_f32 v12, v12, v13
	v_cvt_pk_bf16_f32 v13, v14, v15
	global_store_dwordx2 v[250:251], v[12:13], off offset:-1536
	ds_read_b128 v[80:83], v37 offset:20480
	v_pk_mul_f32 v[8:9], v[8:9], v[164:165] op_sel_hi:[1,0]
	v_pk_mul_f32 v[10:11], v[10:11], v[164:165] op_sel_hi:[1,0]
	v_pk_mul_f32 v[8:9], v[238:239], v[8:9]
	v_pk_mul_f32 v[10:11], v[240:241], v[10:11]
	v_pk_add_f32 v[176:177], v[176:177], 1.0 op_sel_hi:[1,0]
	v_pk_add_f32 v[178:179], v[178:179], 1.0 op_sel_hi:[1,0]
	v_pk_fma_f32 v[8:9], v[176:177], v[8:9], v[84:85]
	v_pk_fma_f32 v[10:11], v[178:179], v[10:11], v[86:87]
	v_cvt_pk_bf16_f32 v8, v8, v9
	v_cvt_pk_bf16_f32 v9, v10, v11
	global_store_dwordx2 v[250:251], v[8:9], off offset:-1024
	ds_read_b128 v[84:87], v37 offset:21504
	v_pk_mul_f32 v[4:5], v[4:5], v[164:165] op_sel_hi:[1,0]
	v_pk_mul_f32 v[6:7], v[6:7], v[164:165] op_sel_hi:[1,0]
	v_pk_mul_f32 v[4:5], v[242:243], v[4:5]
	v_pk_mul_f32 v[6:7], v[244:245], v[6:7]
	v_pk_add_f32 v[180:181], v[180:181], 1.0 op_sel_hi:[1,0]
	v_pk_add_f32 v[182:183], v[182:183], 1.0 op_sel_hi:[1,0]
	v_pk_fma_f32 v[4:5], v[180:181], v[4:5], v[88:89]
	v_pk_fma_f32 v[6:7], v[182:183], v[6:7], v[90:91]
	v_cvt_pk_bf16_f32 v4, v4, v5
	v_cvt_pk_bf16_f32 v5, v6, v7
	global_store_dwordx2 v[250:251], v[4:5], off offset:-512
	ds_read_b128 v[88:91], v37 offset:22528
	v_pk_mul_f32 v[0:1], v[0:1], v[164:165] op_sel_hi:[1,0]
	v_pk_mul_f32 v[2:3], v[2:3], v[164:165] op_sel_hi:[1,0]
	v_pk_mul_f32 v[0:1], v[246:247], v[0:1]
	v_pk_mul_f32 v[2:3], v[248:249], v[2:3]
	v_pk_add_f32 v[184:185], v[184:185], 1.0 op_sel_hi:[1,0]
	v_pk_add_f32 v[186:187], v[186:187], 1.0 op_sel_hi:[1,0]
	v_pk_fma_f32 v[0:1], v[184:185], v[0:1], v[92:93]
	v_pk_fma_f32 v[2:3], v[186:187], v[2:3], v[94:95]
	v_cvt_pk_bf16_f32 v0, v0, v1
	v_cvt_pk_bf16_f32 v1, v2, v3
	global_store_dwordx2 v[250:251], v[0:1], off
	ds_read_b128 v[92:95], v37 offset:23552
	s_waitcnt vmcnt(8)
; __device__ __forceinline__ float bflo(unsigned w) { return __uint_as_float(w << 16); }
; __device__ __forceinline__ float bfhi(unsigned w) { return __uint_as_float(w & 0xffff0000u); }
; __device__ __forceinline__ void row_pass(const RowPass& R, int gw, int ngw, int lane) {
;     ...
;             if (R.update) {
;                 f32x4 y[4]; float ss = 0.f;
; #pragma unroll
;                 for (int j = 0; j < 4; ++j) { const u32x2 w = yw[k][j]; y[j] = (f32x4){bflo(w.x), bfhi(w.x), bflo(w.y), bfhi(w.y)};
;                     ss += (y[j][0] * y[j][0] + y[j][1] * y[j][1]) + (y[j][2] * y[j][2] + y[j][3] * y[j][3]); }
;                 const float rstd = __builtin_amdgcn_rsqf(wave_sum(ss) * (1.0f / DM) + EPS);
;                 const float* gate = R.mod + ((size_t)(R.lg * 9 + bb) * NMOD + R.gi) * DM;
; #pragma unroll
;                 for (int j = 0; j < 4; ++j) { const f32x4 g = *(const f32x4*)(gate + lane * 4 + 256 * j), gp = *(const f32x4*)(R.gpost + lane * 4 + 256 * j);
;                     v[k][j] = v[k][j] + g * (y[j] * rstd * gp); }
;             }
	v_lshlrev_b32_e32 v32, 16, v62
	v_and_b32_e32 v33, 0xffff0000, v62
	v_lshlrev_b32_e32 v34, 16, v63
	v_and_b32_e32 v35, 0xffff0000, v63
	v_pk_mul_f32 v[166:167], v[32:33], v[32:33]
	v_pk_mul_f32 v[168:169], v[34:35], v[34:35]
	v_lshlrev_b32_e32 v32, 16, v60
	v_and_b32_e32 v33, 0xffff0000, v60
	v_lshlrev_b32_e32 v34, 16, v61
	v_and_b32_e32 v35, 0xffff0000, v61
	v_pk_fma_f32 v[166:167], v[32:33], v[32:33], v[166:167]
	v_pk_fma_f32 v[168:169], v[34:35], v[34:35], v[168:169]
	v_lshlrev_b32_e32 v32, 16, v58
	v_and_b32_e32 v33, 0xffff0000, v58
	v_lshlrev_b32_e32 v34, 16, v59
	v_and_b32_e32 v35, 0xffff0000, v59
	v_pk_fma_f32 v[166:167], v[32:33], v[32:33], v[166:167]
	v_pk_fma_f32 v[168:169], v[34:35], v[34:35], v[168:169]
	v_lshlrev_b32_e32 v32, 16, v56
	v_and_b32_e32 v33, 0xffff0000, v56
	v_lshlrev_b32_e32 v34, 16, v57
	v_and_b32_e32 v35, 0xffff0000, v57
	v_pk_fma_f32 v[166:167], v[32:33], v[32:33], v[166:167]
	v_pk_fma_f32 v[168:169], v[34:35], v[34:35], v[168:169]
	v_pk_add_f32 v[166:167], v[166:167], v[168:169]
	s_nop 0
	v_add_f32_e32 v164, v166, v167
	v_mov_b32_e32 v165, v164
	s_nop 1
	v_permlane32_swap_b32_e32 v165, v164
	v_add_f32_e32 v164, v164, v165
	v_mov_b32_e32 v165, v164
	s_nop 1
	v_permlane16_swap_b32_e32 v165, v164
	v_add_f32_e32 v164, v164, v165
	s_nop 1
	v_add_f32_dpp v164, v164, v164 row_ror:8 row_mask:0xf bank_mask:0xf
	s_nop 1
	v_add_f32_dpp v164, v164, v164 row_ror:4 row_mask:0xf bank_mask:0xf
	s_nop 1
	v_add_f32_dpp v164, v164, v164 row_ror:2 row_mask:0xf bank_mask:0xf
	s_nop 1
	v_add_f32_dpp v164, v164, v164 row_ror:1 row_mask:0xf bank_mask:0xf
	s_nop 0
	v_fmamk_f32 v164, v164, 0x3a800000, v200
	v_rsq_f32_e32 v164, v164
	v_lshlrev_b32_e32 v32, 16, v62
	v_and_b32_e32 v33, 0xffff0000, v62
	v_lshlrev_b32_e32 v34, 16, v63
	v_and_b32_e32 v35, 0xffff0000, v63
	v_pk_mul_f32 v[32:33], v[32:33], v[164:165] op_sel_hi:[1,0]
	v_pk_mul_f32 v[34:35], v[34:35], v[164:165] op_sel_hi:[1,0]
	v_pk_mul_f32 v[32:33], v[218:219], v[32:33]
	v_pk_mul_f32 v[34:35], v[220:221], v[34:35]
	s_waitcnt lgkmcnt(11)
	v_pk_fma_f32 v[16:17], v[188:189], v[32:33], v[16:17]
	v_pk_fma_f32 v[18:19], v[190:191], v[34:35], v[18:19]
	global_store_dwordx4 v160, v[16:19], s[64:65] nt
	v_lshlrev_b32_e32 v32, 16, v60
	v_and_b32_e32 v33, 0xffff0000, v60
	v_lshlrev_b32_e32 v34, 16, v61
	v_and_b32_e32 v35, 0xffff0000, v61
	v_pk_mul_f32 v[32:33], v[32:33], v[164:165] op_sel_hi:[1,0]
	v_pk_mul_f32 v[34:35], v[34:35], v[164:165] op_sel_hi:[1,0]
	v_pk_mul_f32 v[32:33], v[222:223], v[32:33]
	v_pk_mul_f32 v[34:35], v[224:225], v[34:35]
	s_waitcnt lgkmcnt(10)
	v_pk_fma_f32 v[20:21], v[192:193], v[32:33], v[20:21]
	v_pk_fma_f32 v[22:23], v[194:195], v[34:35], v[22:23]
	global_store_dwordx4 v160, v[20:23], s[64:65] offset:1024 nt
	v_lshlrev_b32_e32 v32, 16, v58
	v_and_b32_e32 v33, 0xffff0000, v58
	v_lshlrev_b32_e32 v34, 16, v59
	v_and_b32_e32 v35, 0xffff0000, v59
	v_pk_mul_f32 v[32:33], v[32:33], v[164:165] op_sel_hi:[1,0]
	v_pk_mul_f32 v[34:35], v[34:35], v[164:165] op_sel_hi:[1,0]
	v_pk_mul_f32 v[32:33], v[226:227], v[32:33]
	v_pk_mul_f32 v[34:35], v[228:229], v[34:35]
	s_waitcnt lgkmcnt(9)
	v_pk_fma_f32 v[24:25], v[196:197], v[32:33], v[24:25]
	v_pk_fma_f32 v[26:27], v[198:199], v[34:35], v[26:27]
	global_store_dwordx4 v160, v[24:27], s[64:65] offset:2048 nt
	v_lshlrev_b32_e32 v32, 16, v56
	v_and_b32_e32 v33, 0xffff0000, v56
	v_lshlrev_b32_e32 v34, 16, v57
	v_and_b32_e32 v35, 0xffff0000, v57
	v_pk_mul_f32 v[32:33], v[32:33], v[164:165] op_sel_hi:[1,0]
	v_pk_mul_f32 v[34:35], v[34:35], v[164:165] op_sel_hi:[1,0]
	v_pk_mul_f32 v[32:33], v[230:231], v[32:33]
	v_pk_mul_f32 v[34:35], v[232:233], v[34:35]
	s_waitcnt lgkmcnt(8)
; __device__ __forceinline__ unsigned pk2(float lo, float hi) { return pg8::cvt_pk_bf16(lo, hi); }
; __device__ __forceinline__ void row_pass(const RowPass& R, int gw, int ngw, int lane) {
;     ...
;             if (R.norm_out) {
;                 float ss = 0.f;
; #pragma unroll
;                 for (int j = 0; j < 4; ++j) ss += (v[k][j][0] * v[k][j][0] + v[k][j][1] * v[k][j][1]) + (v[k][j][2] * v[k][j][2] + v[k][j][3] * v[k][j][3]);
;                 const float rstd = __builtin_amdgcn_rsqf(wave_sum(ss) * (1.0f / DM) + EPS);
;                 const float* shift = R.mod + ((size_t)(R.ln * 9 + bb) * NMOD + R.si) * DM; const float* scale = shift + DM;
;                 bf16* hr = R.H + (size_t)row * DM;
; #pragma unroll
;                 for (int j = 0; j < 4; ++j) { const f32x4 gp = *(const f32x4*)(R.gpre + lane * 4 + 256 * j), sh = *(const f32x4*)(shift + lane * 4 + 256 * j), sc = *(const f32x4*)(scale + lane * 4 + 256 * j);
;                     const f32x4 hv = (v[k][j] * rstd * gp) * (sc + 1.0f) + sh;
;                     u32x2 w; w.x = pk2(hv[0], hv[1]); w.y = pk2(hv[2], hv[3]); *(u32x2*)(hr + lane * 4 + 256 * j) = w; }
;             }
;         }
	v_pk_fma_f32 v[28:29], v[96:97], v[32:33], v[28:29]
	v_pk_fma_f32 v[30:31], v[98:99], v[34:35], v[30:31]
	global_store_dwordx4 v160, v[28:31], s[64:65] offset:3072 nt
	v_pk_mul_f32 v[166:167], v[16:17], v[16:17]
	v_pk_mul_f32 v[168:169], v[18:19], v[18:19]
	v_pk_fma_f32 v[166:167], v[20:21], v[20:21], v[166:167]
	v_pk_fma_f32 v[168:169], v[22:23], v[22:23], v[168:169]
	v_pk_fma_f32 v[166:167], v[24:25], v[24:25], v[166:167]
	v_pk_fma_f32 v[168:169], v[26:27], v[26:27], v[168:169]
	v_pk_fma_f32 v[166:167], v[28:29], v[28:29], v[166:167]
	v_pk_fma_f32 v[168:169], v[30:31], v[30:31], v[168:169]
	v_pk_add_f32 v[166:167], v[166:167], v[168:169]
	s_nop 0
	v_add_f32_e32 v164, v166, v167
	v_mov_b32_e32 v165, v164
	s_nop 1
	v_permlane32_swap_b32_e32 v165, v164
	v_add_f32_e32 v164, v164, v165
	v_mov_b32_e32 v165, v164
	s_nop 1
	v_permlane16_swap_b32_e32 v165, v164
	v_add_f32_e32 v164, v164, v165
	s_nop 1
	v_add_f32_dpp v164, v164, v164 row_ror:8 row_mask:0xf bank_mask:0xf
	s_nop 1
	v_add_f32_dpp v164, v164, v164 row_ror:4 row_mask:0xf bank_mask:0xf
	s_nop 1
	v_add_f32_dpp v164, v164, v164 row_ror:2 row_mask:0xf bank_mask:0xf
	s_nop 1
	v_add_f32_dpp v164, v164, v164 row_ror:1 row_mask:0xf bank_mask:0xf
	s_nop 0
	v_fmamk_f32 v164, v164, 0x3a800000, v200
	v_rsq_f32_e32 v164, v164
	s_nop 0
	v_pk_mul_f32 v[16:17], v[16:17], v[164:165] op_sel_hi:[1,0]
	v_pk_mul_f32 v[18:19], v[18:19], v[164:165] op_sel_hi:[1,0]
	v_pk_mul_f32 v[16:17], v[234:235], v[16:17]
	v_pk_mul_f32 v[18:19], v[236:237], v[18:19]
	s_waitcnt lgkmcnt(3)
	v_pk_add_f32 v[80:81], v[80:81], 1.0 op_sel_hi:[1,0]
	v_pk_add_f32 v[82:83], v[82:83], 1.0 op_sel_hi:[1,0]
	v_pk_fma_f32 v[16:17], v[80:81], v[16:17], v[64:65]
	v_pk_fma_f32 v[18:19], v[82:83], v[18:19], v[66:67]
	v_cvt_pk_bf16_f32 v16, v16, v17
	v_cvt_pk_bf16_f32 v17, v18, v19
	global_store_dwordx2 v[252:253], v[16:17], off
	v_pk_mul_f32 v[20:21], v[20:21], v[164:165] op_sel_hi:[1,0]
	v_pk_mul_f32 v[22:23], v[22:23], v[164:165] op_sel_hi:[1,0]
	v_pk_mul_f32 v[20:21], v[238:239], v[20:21]
	v_pk_mul_f32 v[22:23], v[240:241], v[22:23]
	s_waitcnt lgkmcnt(2)
	v_pk_add_f32 v[84:85], v[84:85], 1.0 op_sel_hi:[1,0]
	v_pk_add_f32 v[86:87], v[86:87], 1.0 op_sel_hi:[1,0]
	v_pk_fma_f32 v[20:21], v[84:85], v[20:21], v[68:69]
	v_pk_fma_f32 v[22:23], v[86:87], v[22:23], v[70:71]
	v_cvt_pk_bf16_f32 v20, v20, v21
	v_cvt_pk_bf16_f32 v21, v22, v23
	global_store_dwordx2 v[252:253], v[20:21], off offset:512
	v_pk_mul_f32 v[24:25], v[24:25], v[164:165] op_sel_hi:[1,0]
	v_pk_mul_f32 v[26:27], v[26:27], v[164:165] op_sel_hi:[1,0]
	v_pk_mul_f32 v[24:25], v[242:243], v[24:25]
	v_pk_mul_f32 v[26:27], v[244:245], v[26:27]
	s_waitcnt lgkmcnt(1)
	v_pk_add_f32 v[88:89], v[88:89], 1.0 op_sel_hi:[1,0]
	v_pk_add_f32 v[90:91], v[90:91], 1.0 op_sel_hi:[1,0]
	v_pk_fma_f32 v[24:25], v[88:89], v[24:25], v[72:73]
	v_pk_fma_f32 v[26:27], v[90:91], v[26:27], v[74:75]
	v_cvt_pk_bf16_f32 v24, v24, v25
	v_cvt_pk_bf16_f32 v25, v26, v27
	global_store_dwordx2 v[252:253], v[24:25], off offset:1024
	v_pk_mul_f32 v[28:29], v[28:29], v[164:165] op_sel_hi:[1,0]
	v_pk_mul_f32 v[30:31], v[30:31], v[164:165] op_sel_hi:[1,0]
	v_pk_mul_f32 v[28:29], v[246:247], v[28:29]
	v_pk_mul_f32 v[30:31], v[248:249], v[30:31]
	s_waitcnt lgkmcnt(0)
	v_pk_add_f32 v[92:93], v[92:93], 1.0 op_sel_hi:[1,0]
	v_pk_add_f32 v[94:95], v[94:95], 1.0 op_sel_hi:[1,0]
	v_pk_fma_f32 v[28:29], v[92:93], v[28:29], v[76:77]
	v_pk_fma_f32 v[30:31], v[94:95], v[30:31], v[78:79]
	v_cvt_pk_bf16_f32 v28, v28, v29
	v_cvt_pk_bf16_f32 v29, v30, v31
	global_store_dwordx2 v[252:253], v[28:29], off offset:1536
	s_xor_b32 s93, s93, 0x6000
	s_branch .LBB0_148
